# e1+e4+e6 plus e7: L2 prefetch loads two steps ahead in HGRN chunk-state loop, tail wait vmcnt(4)
# baseline (speedup 1.0000x reference)
; __device__ __forceinline__ void hgrn_state_item64(const float* __restrict__ LOGF, const bf16* __restrict__ V, int row0, int nsteps, int h, bf16* __restrict__ Sout, float* __restrict__ Dout, char* lds) {
;     ...
; #pragma unroll 1
;     for (int s = 0; s < nsteps; ++s) {
;         if (s + 2 < nsteps) HG_DMA(s + 2, s & 1);
;         hgrn_mma64(lds, s, kc, tq, vf_cur, S);
.LBB0_2184:
	s_bitcmp1_b32 s4, 0
	s_cselect_b32 s5, 0xc000, 0
	s_add_i32 s5, s10, s5
	v_lshl_add_u64 v[66:67], v[54:55], 0, s[20:21]
	s_mov_b64 s[6:7], 0x28580000
	v_lshl_add_u64 v[68:69], v[66:67], 0, s[6:7]
	s_mov_b32 m0, s5
	s_mov_b64 s[6:7], 0x28584000
	global_load_lds_dwordx4 v[68:69], off
	v_lshl_add_u64 v[68:69], v[66:67], 0, s[6:7]
	s_add_i32 m0, s5, 0x400
	s_mov_b64 s[6:7], 0x30780000
	global_load_lds_dwordx4 v[68:69], off
	s_add_i32 m0, s5, 0x8000
	v_lshl_add_u64 v[68:69], v[66:67], 0, s[6:7]
	s_mov_b64 s[6:7], 0x30784000
	global_load_lds_dwordx4 v[68:69], off
	v_lshl_add_u64 v[66:67], v[66:67], 0, s[6:7]
	s_add_i32 m0, s5, 0x8400
	s_nop 0
	global_load_lds_dwordx4 v[66:67], off
	v_lshl_add_u64 v[134:135], v[54:55], 0, s[20:21]
	s_mov_b64 s[6:7], 0x28600000
	v_lshl_add_u64 v[136:137], v[134:135], 0, s[6:7]
	global_load_dword v132, v[136:137], off
	s_mov_b64 s[6:7], 0x28604000
	v_lshl_add_u64 v[136:137], v[134:135], 0, s[6:7]
	global_load_dword v132, v[136:137], off
	s_mov_b64 s[6:7], 0x30800000
	v_lshl_add_u64 v[136:137], v[134:135], 0, s[6:7]
	global_load_dword v132, v[136:137], off
	s_mov_b64 s[6:7], 0x30804000
	v_lshl_add_u64 v[136:137], v[134:135], 0, s[6:7]
	global_load_dword v132, v[136:137], off

; __device__ __forceinline__ unsigned cvt_pk_bf16(float lo, float hi) { unsigned r; asm volatile("v_cvt_pk_bf16_f32 %0, %1, %2" : "=v"(r) : "v"(lo), "v"(hi)); return r; }
; __device__ __forceinline__ void hgrn_state_item64(const float* __restrict__ LOGF, const bf16* __restrict__ V, int row0, int nsteps, int h, bf16* __restrict__ Sout, float* __restrict__ Dout, char* lds) {
;     ...
;         asm volatile("s_waitcnt vmcnt(0) lgkmcnt(0)" ::: "memory"); __builtin_amdgcn_s_barrier(); asm volatile("" ::: "memory");
;         vf_cur[0] = vf_nxt[0]; vf_cur[1] = vf_nxt[1];
;     }
;     ...
; #pragma unroll
;     for (int kb = 0; kb < 8; ++kb)
; #pragma unroll
;         for (int i = 0; i < 4; ++i) Sout[(size_t)(16 * kb + 4 * tq + i) * 128 + 16 * w + kc] = (bf16)(cvt_pk_bf16(S[kb][i], 0.f) & 0xffffu);
;     if (tq == 0) Dout[16 * w + kc] = __builtin_amdgcn_exp2f(gsum);
.LBB0_2199:
	s_waitcnt vmcnt(4) lgkmcnt(0)
	s_barrier
	s_add_u32 s20, s20, 0x40000
	s_addc_u32 s21, s21, 0
	s_cmp_eq_u32 s20, 0x400000
	s_cbranch_scc0 .LBB0_2183
	s_waitcnt vmcnt(0)
	s_lshl_b32 s4, s19, 4
	s_add_i32 s20, s4, s47
	s_ashr_i32 s21, s20, 31
	s_lshl_b64 s[4:5], s[20:21], 15
	s_add_u32 s6, s42, s4
	s_addc_u32 s7, s43, s5
	s_ashr_i32 s19, s18, 31
	s_lshl_b64 s[4:5], s[18:19], 1
	s_add_u32 s4, s6, s4
	s_addc_u32 s5, s7, s5
	v_lshlrev_b32_e32 v2, 1, v56
	v_lshl_add_u64 v[4:5], s[4:5], 0, v[2:3]
	v_lshlrev_b32_e32 v2, 10, v53
	v_cvt_pk_bf16_f32 v6, v12, v3
	v_lshl_add_u64 v[4:5], v[4:5], 0, v[2:3]
	global_store_short v[4:5], v6, off
	v_cvt_pk_bf16_f32 v2, v13, v3
	v_add_co_u32_e32 v6, vcc, s97, v4
	global_store_short v[4:5], v2, off offset:256
	v_cvt_pk_bf16_f32 v2, v14, v3
	s_nop 0
	v_addc_co_u32_e32 v7, vcc, 0, v5, vcc
	global_store_short v[4:5], v2, off offset:512
	v_cvt_pk_bf16_f32 v2, v15, v3
	v_add_co_u32_e32 v8, vcc, s75, v4
	global_store_short v[4:5], v2, off offset:768
	v_cvt_pk_bf16_f32 v2, v40, v3
	s_nop 0
	v_addc_co_u32_e32 v9, vcc, 0, v5, vcc
	global_store_short v[8:9], v2, off offset:-4096
	v_cvt_pk_bf16_f32 v2, v41, v3
	global_store_short v[6:7], v2, off offset:256
	v_cvt_pk_bf16_f32 v2, v42, v3
	global_store_short v[6:7], v2, off offset:512
	v_cvt_pk_bf16_f32 v2, v43, v3
	global_store_short v[6:7], v2, off offset:768
	v_cvt_pk_bf16_f32 v2, v36, v3
	s_movk_i32 s4, 0x3000
	global_store_short v[8:9], v2, off
	v_cvt_pk_bf16_f32 v2, v37, v3
	v_add_co_u32_e32 v6, vcc, s4, v4
	global_store_short v[8:9], v2, off offset:256
	v_cvt_pk_bf16_f32 v2, v38, v3
	s_nop 0
	v_addc_co_u32_e32 v7, vcc, 0, v5, vcc
	s_movk_i32 s4, 0x4000
	global_store_short v[8:9], v2, off offset:512
	v_cvt_pk_bf16_f32 v2, v39, v3
	global_store_short v[8:9], v2, off offset:768
	v_add_co_u32_e32 v8, vcc, s4, v4
	v_cvt_pk_bf16_f32 v2, v32, v3
	s_movk_i32 s4, 0x5000
	s_nop 0
	v_addc_co_u32_e32 v9, vcc, 0, v5, vcc
	global_store_short v[8:9], v2, off offset:-4096
	v_cvt_pk_bf16_f32 v2, v33, v3
	global_store_short v[6:7], v2, off offset:256
	v_cvt_pk_bf16_f32 v2, v34, v3
	global_store_short v[6:7], v2, off offset:512
	v_cvt_pk_bf16_f32 v2, v35, v3
	global_store_short v[6:7], v2, off offset:768
	v_cvt_pk_bf16_f32 v2, v28, v3
	global_store_short v[8:9], v2, off
	v_cvt_pk_bf16_f32 v2, v29, v3
	v_add_co_u32_e32 v6, vcc, s4, v4
	global_store_short v[8:9], v2, off offset:256
	v_cvt_pk_bf16_f32 v2, v30, v3
	s_nop 0
	v_addc_co_u32_e32 v7, vcc, 0, v5, vcc
	s_movk_i32 s4, 0x6000
	global_store_short v[8:9], v2, off offset:512
	v_cvt_pk_bf16_f32 v2, v31, v3
	global_store_short v[8:9], v2, off offset:768
	v_add_co_u32_e32 v8, vcc, s4, v4
	v_cvt_pk_bf16_f32 v2, v24, v3
	s_nop 1
	v_addc_co_u32_e32 v9, vcc, 0, v5, vcc
	global_store_short v[8:9], v2, off offset:-4096
	v_cvt_pk_bf16_f32 v2, v25, v3
	global_store_short v[6:7], v2, off offset:256
	v_cvt_pk_bf16_f32 v2, v26, v3
	global_store_short v[6:7], v2, off offset:512
	v_cvt_pk_bf16_f32 v2, v27, v3
	global_store_short v[6:7], v2, off offset:768
	v_cvt_pk_bf16_f32 v2, v20, v3
	global_store_short v[8:9], v2, off
	v_cvt_pk_bf16_f32 v2, v21, v3
	global_store_short v[8:9], v2, off offset:256
	v_cvt_pk_bf16_f32 v2, v22, v3
	global_store_short v[8:9], v2, off offset:512
	v_cvt_pk_bf16_f32 v2, v23, v3
	v_add_co_u32_e32 v4, vcc, 0x7000, v4
	global_store_short v[8:9], v2, off offset:768
	v_cvt_pk_bf16_f32 v2, v16, v3
	s_nop 0
	v_addc_co_u32_e32 v5, vcc, 0, v5, vcc
	global_store_short v[4:5], v2, off
	v_cvt_pk_bf16_f32 v2, v17, v3
	global_store_short v[4:5], v2, off offset:256
	v_cvt_pk_bf16_f32 v2, v18, v3
	v_cmp_eq_u32_e32 vcc, 0, v53
	global_store_short v[4:5], v2, off offset:512
	v_cvt_pk_bf16_f32 v2, v19, v3
	global_store_short v[4:5], v2, off offset:768
	s_and_saveexec_b64 s[18:19], vcc
	s_cbranch_execz .LBB0_2169
	s_lshl_b64 s[4:5], s[20:21], 9
	v_exp_f32_e32 v2, v58
	s_add_u32 s4, s44, s4
	s_addc_u32 s5, s45, s5
	v_ashrrev_i32_e32 v53, 31, v52
	v_lshl_add_u64 v[4:5], v[52:53], 2, s[4:5]
	global_store_dword v[4:5], v2, off
	s_branch .LBB0_2169
